# packed f32 ops split in S5 prefix loop and attention unit epilogues
# baseline (speedup 1.0000x reference)
.LBB0_440:
	v_add_co_u32_e32 v8, vcc, 0xffffe900, v2
	v_mul_f32_e64 v10, v0, v6
	v_mul_f32_e64 v11, v1, v7
	v_addc_co_u32_e32 v9, vcc, -1, v3, vcc
	v_add_co_u32_e32 v14, vcc, 0xffffea00, v2
	v_sub_f32_e32 v60, v10, v11
	s_nop 0
	v_addc_co_u32_e32 v15, vcc, -1, v3, vcc
	v_add_co_u32_e32 v10, vcc, 0xffffeb00, v2
	v_mul_f32_e64 v12, v0, v7
	v_mul_f32_e64 v13, v1, v6
	v_addc_co_u32_e32 v11, vcc, -1, v3, vcc
	v_add_f32_e32 v61, v12, v13
	v_add_co_u32_e32 v12, vcc, 0xffffec00, v2
	global_load_dword v62, v[8:9], off
	global_load_dword v63, v[14:15], off
	v_addc_co_u32_e32 v13, vcc, -1, v3, vcc
	v_add_co_u32_e32 v16, vcc, 0xffffed00, v2
	global_load_dword v18, v[10:11], off
	global_load_dword v19, v[12:13], off
	v_addc_co_u32_e32 v17, vcc, -1, v3, vcc
	v_add_co_u32_e32 v20, vcc, 0xffffee00, v2
	s_movk_i32 s2, 0xfc00
	s_nop 0
	v_addc_co_u32_e32 v21, vcc, -1, v3, vcc
	v_add_co_u32_e32 v22, vcc, 0xffffef00, v2
	global_load_dword v64, v[16:17], off
	global_load_dword v65, v[20:21], off
	v_addc_co_u32_e32 v23, vcc, -1, v3, vcc
	v_add_co_u32_e32 v24, vcc, 0xfffff000, v2
	s_add_i32 s4, s4, 12
	s_nop 0
	v_addc_co_u32_e32 v25, vcc, -1, v3, vcc
	v_add_co_u32_e32 v26, vcc, 0xfffff100, v2
	global_load_dword v28, v[22:23], off
	global_load_dword v29, v[24:25], off
	v_addc_co_u32_e32 v27, vcc, -1, v3, vcc
	v_add_co_u32_e32 v30, vcc, 0xfffff200, v2
	global_store_dword v[8:9], v6, off
	global_store_dword v[14:15], v7, off
	v_addc_co_u32_e32 v31, vcc, -1, v3, vcc
	v_add_co_u32_e32 v8, vcc, 0xfffff300, v2
	global_load_dword v66, v[26:27], off
	global_load_dword v67, v[30:31], off
	v_addc_co_u32_e32 v9, vcc, -1, v3, vcc
	v_add_co_u32_e32 v14, vcc, 0xfffff400, v2
	s_cmpk_lt_u32 s4, 0x78
	s_nop 0
	v_addc_co_u32_e32 v15, vcc, -1, v3, vcc
	v_add_co_u32_e32 v32, vcc, 0xfffff500, v2
	global_load_dword v34, v[8:9], off
	global_load_dword v35, v[14:15], off
	v_addc_co_u32_e32 v33, vcc, -1, v3, vcc
	v_add_co_u32_e32 v36, vcc, 0xfffff600, v2
	s_waitcnt vmcnt(0) lgkmcnt(0)
	v_add_f32_e32 v60, v60, v62
	v_addc_co_u32_e32 v37, vcc, -1, v3, vcc
	v_add_co_u32_e32 v38, vcc, 0xfffff700, v2
	global_load_dword v68, v[32:33], off
	global_load_dword v69, v[36:37], off
	v_addc_co_u32_e32 v39, vcc, -1, v3, vcc
	v_add_co_u32_e32 v40, vcc, 0xfffff800, v2
	v_add_f32_e32 v62, v61, v63
	s_nop 0
	v_addc_co_u32_e32 v41, vcc, -1, v3, vcc
	v_add_co_u32_e32 v42, vcc, 0xfffff900, v2
	global_load_dword v44, v[38:39], off
	global_load_dword v45, v[40:41], off
	v_addc_co_u32_e32 v43, vcc, -1, v3, vcc
	v_add_co_u32_e32 v46, vcc, 0xfffffa00, v2
	s_nop 1
	v_addc_co_u32_e32 v47, vcc, -1, v3, vcc
	v_add_co_u32_e32 v48, vcc, 0xfffffb00, v2
	global_load_dword v70, v[42:43], off
	global_load_dword v71, v[46:47], off
	v_addc_co_u32_e32 v49, vcc, -1, v3, vcc
	v_add_co_u32_e32 v50, vcc, s2, v2
	s_movk_i32 s2, 0xfe00
	s_nop 0
	v_addc_co_u32_e32 v51, vcc, -1, v3, vcc
	v_add_co_u32_e32 v52, vcc, 0xfffffd00, v2
	global_load_dword v54, v[48:49], off
	global_load_dword v55, v[50:51], off
	v_addc_co_u32_e32 v53, vcc, -1, v3, vcc
	v_add_co_u32_e32 v56, vcc, s2, v2
	s_mov_b64 s[2:3], 0x1800
	s_nop 0
	v_addc_co_u32_e32 v57, vcc, -1, v3, vcc
	global_load_dword v72, v[52:53], off
	global_load_dword v73, v[56:57], off
	v_add_co_u32_e32 v58, vcc, 0xffffff00, v2
	s_nop 1
	v_addc_co_u32_e32 v59, vcc, -1, v3, vcc
	global_load_dword v6, v[58:59], off
	global_load_dword v7, v[2:3], off
	s_nop 0
	global_store_dword v[10:11], v60, off
	global_store_dword v[12:13], v62, off
	v_fma_f32 v10, -v4, v62, v18
	v_fma_f32 v11, v5, v62, v19
	v_fma_f32 v10, v0, v60, v10
	v_fma_f32 v11, v1, v60, v11
	global_store_dword v[16:17], v10, off
	global_store_dword v[20:21], v11, off
	v_mul_f32_e64 v12, v0, v10
	v_mul_f32_e64 v13, v1, v11
	v_pk_mul_f32 v[10:11], v[0:1], v[10:11] op_sel:[0,1] op_sel_hi:[1,0]
	v_sub_f32_e32 v12, v12, v13
	v_add_f32_e32 v11, v10, v11
	v_add_f32_e32 v10, v12, v64
	v_add_f32_e32 v12, v11, v65
	global_store_dword v[22:23], v10, off
	global_store_dword v[24:25], v12, off
	v_fma_f32 v13, v5, v12, v29
	v_mul_f32_e64 v12, v4, v12
	v_fma_f32 v16, v0, v10, -v12
	v_fma_f32 v11, v1, v10, v13
	v_add_f32_e64 v10, v16, v28
	global_store_dword v[26:27], v10, off
	global_store_dword v[30:31], v11, off
	v_mul_f32_e64 v12, v0, v10
	v_mul_f32_e64 v13, v1, v11
	v_pk_mul_f32 v[10:11], v[0:1], v[10:11] op_sel:[0,1] op_sel_hi:[1,0]
	v_sub_f32_e32 v12, v12, v13
	v_add_f32_e32 v11, v10, v11
	v_add_f32_e32 v10, v12, v66
	v_add_f32_e32 v12, v11, v67
	global_store_dword v[8:9], v10, off
	global_store_dword v[14:15], v12, off
	v_fma_f32 v8, -v4, v12, v34
	v_fma_f32 v9, v5, v12, v35
	v_fma_f32 v8, v0, v10, v8
	v_fma_f32 v9, v1, v10, v9
	global_store_dword v[32:33], v8, off
	global_store_dword v[36:37], v9, off
	v_mul_f32_e64 v10, v0, v8
	v_mul_f32_e64 v11, v1, v9
	v_pk_mul_f32 v[8:9], v[0:1], v[8:9] op_sel:[0,1] op_sel_hi:[1,0]
	v_sub_f32_e32 v10, v10, v11
	v_add_f32_e32 v9, v8, v9
	s_waitcnt vmcnt(0) lgkmcnt(0)
	v_add_f32_e32 v8, v10, v68
	v_add_f32_e32 v10, v9, v69
	global_store_dword v[38:39], v8, off
	global_store_dword v[40:41], v10, off
	v_fma_f32 v11, v5, v10, v45
	v_mul_f32_e64 v10, v4, v10
	v_fma_f32 v12, v0, v8, -v10
	v_fma_f32 v9, v1, v8, v11
	v_add_f32_e64 v8, v12, v44
	global_store_dword v[42:43], v8, off
	global_store_dword v[46:47], v9, off
	v_mul_f32_e64 v10, v0, v8
	v_mul_f32_e64 v11, v1, v9
	v_pk_mul_f32 v[8:9], v[0:1], v[8:9] op_sel:[0,1] op_sel_hi:[1,0]
	v_sub_f32_e32 v10, v10, v11
	v_add_f32_e32 v9, v8, v9
	v_add_f32_e32 v8, v10, v70
	v_add_f32_e32 v10, v9, v71
	global_store_dword v[48:49], v8, off
	global_store_dword v[50:51], v10, off
	v_fma_f32 v11, v5, v10, v55
	v_mul_f32_e64 v10, v4, v10
	v_fma_f32 v12, v0, v8, -v10
	v_fma_f32 v9, v1, v8, v11
	v_add_f32_e64 v8, v12, v54
	global_store_dword v[52:53], v8, off
	global_store_dword v[56:57], v9, off
	v_mul_f32_e64 v10, v0, v8
	v_mul_f32_e64 v11, v1, v9
	v_pk_mul_f32 v[8:9], v[0:1], v[8:9] op_sel:[0,1] op_sel_hi:[1,0]
	v_sub_f32_e32 v10, v10, v11
	v_add_f32_e32 v9, v8, v9
	v_add_f32_e32 v8, v10, v72
	v_add_f32_e32 v10, v9, v73
	global_store_dword v[58:59], v8, off
	global_store_dword v[2:3], v10, off
	v_fma_f32 v11, v5, v10, v7
	v_mul_f32_e64 v10, v4, v10
	v_lshl_add_u64 v[2:3], v[2:3], 0, s[2:3]
	v_fma_f32 v12, v0, v8, -v10
	v_fma_f32 v7, v1, v8, v11
	v_fma_f32 v8, v0, v8, v10
	v_add_f32_e64 v6, v12, v6
	s_cbranch_scc1 .LBB0_440

.LBB0_487:
	v_and_b32_e32 v36, 64, v188
	v_xor_b32_e32 v33, 32, v188
	v_add_u32_e32 v36, 64, v36
	v_cmp_lt_i32_e32 vcc, v33, v36
	s_lshl_b32 s0, s7, 6
	s_lshl_b32 s84, s0, 1
	v_cndmask_b32_e32 v33, v188, v33, vcc
	v_lshlrev_b32_e32 v33, 2, v33
	ds_bpermute_b32 v33, v33, v208
	v_lshl_add_u64 v[34:35], v[178:179], 0, s[84:85]
	v_lshl_add_u64 v[34:35], v[34:35], 0, v[112:113]
	s_mov_b64 s[0:1], 0x1400
	s_mov_b32 s64, s38
	s_waitcnt lgkmcnt(0)
	v_add_f32_e32 v36, v208, v33
	v_mov_b32_e32 v33, v113
	v_lshl_add_u64 v[34:35], v[32:33], 1, v[34:35]
	v_lshl_add_u64 v[32:33], v[34:35], 0, s[0:1]
	s_movk_i32 s0, 0x1000
	v_add_co_u32_e32 v50, vcc, s0, v34
	v_div_scale_f32 v37, s[0:1], v36, v36, 1.0
	s_nop 0
	v_addc_co_u32_e32 v51, vcc, 0, v35, vcc
	global_load_dwordx2 v[52:53], v[50:51], off offset:1024
	global_load_dwordx2 v[48:49], v[32:33], off offset:16
	global_load_dwordx2 v[46:47], v[32:33], off offset:32
	global_load_dwordx2 v[44:45], v[32:33], off offset:48
	global_load_dwordx2 v[42:43], v[32:33], off offset:64
	global_load_dwordx2 v[40:41], v[32:33], off offset:80
	global_load_dwordx2 v[38:39], v[32:33], off offset:96
	global_load_dwordx2 v[34:35], v[32:33], off offset:112
	v_rcp_f32_e32 v54, v37
	v_mov_b32_e32 v191, v204
	s_mov_b32 s63, s39
	s_mov_b32 s62, s40
	v_fma_f32 v55, -v37, v54, 1.0
	v_fmac_f32_e32 v54, v55, v54
	v_div_scale_f32 v55, vcc, 1.0, v36, 1.0
	v_mul_f32_e32 v56, v55, v54
	v_fma_f32 v57, -v37, v56, v55
	v_fmac_f32_e32 v56, v57, v54
	v_fma_f32 v37, -v37, v56, v55
	v_div_fmas_f32 v37, v37, v54, v56
	v_div_fixup_f32 v36, v37, v36, 1.0
	s_mov_b32 s65, s41
	v_mov_b32_e32 v192, v202
	v_mov_b32_e32 v193, v203
	s_waitcnt vmcnt(0) lgkmcnt(0)
	v_lshlrev_b32_e32 v54, 16, v52
	v_mul_f32_e32 v37, 0xbfb8aa3b, v54
	v_exp_f32_e32 v37, v37
	v_and_b32_e32 v55, 0xffff0000, v52
	v_lshlrev_b32_e32 v52, 16, v53
	v_and_b32_e32 v53, 0xffff0000, v53
	v_add_f32_e32 v37, 1.0, v37
	v_rcp_f32_e32 v56, v37
	v_mul_f32_e64 v16, v16, v36
	v_mul_f32_e64 v17, v17, v36
	v_mul_f32_e32 v37, 0xbfb8aa3b, v55
	v_exp_f32_e32 v37, v37
	s_nop 0
	v_add_f32_e32 v37, 1.0, v37
	v_rcp_f32_e32 v57, v37
	v_mul_f32_e32 v37, 0xbfb8aa3b, v52
	v_exp_f32_e32 v37, v37
	v_mul_f32_e64 v54, v56, v54
	v_mul_f32_e64 v55, v57, v55
	v_mul_f32_e64 v16, v16, v54
	v_mul_f32_e64 v17, v17, v55
	v_add_f32_e32 v37, 1.0, v37
	v_rcp_f32_e32 v54, v37
	v_mul_f32_e64 v18, v18, v36
	v_mul_f32_e64 v19, v19, v36
	v_mul_f32_e32 v37, 0xbfb8aa3b, v53
	v_exp_f32_e32 v37, v37
	v_cvt_pk_bf16_f32 v16, v16, v17
	v_add_f32_e32 v37, 1.0, v37
	v_rcp_f32_e32 v55, v37
	v_mul_f32_e64 v20, v20, v36
	v_mul_f32_e64 v21, v21, v36
	v_mul_f32_e64 v22, v22, v36
	v_mul_f32_e64 v23, v23, v36
	v_mul_f32_e64 v0, v0, v36
	v_mul_f32_e64 v1, v1, v36
	v_mul_f32_e64 v52, v54, v52
	v_mul_f32_e64 v53, v55, v53
	v_mul_f32_e64 v2, v2, v36
	v_mul_f32_e64 v3, v3, v36
	v_mul_f32_e64 v18, v18, v52
	v_mul_f32_e64 v19, v19, v53
	v_mul_f32_e64 v4, v4, v36
	v_mul_f32_e64 v5, v5, v36
	v_cvt_pk_bf16_f32 v17, v18, v19
	global_store_dwordx2 v[50:51], v[16:17], off offset:1024
	v_lshlrev_b32_e32 v16, 16, v48
	v_and_b32_e32 v17, 0xffff0000, v48
	v_mul_f32_e32 v18, 0xbfb8aa3b, v16
	v_mul_f32_e32 v19, 0xbfb8aa3b, v17
	v_exp_f32_e32 v18, v18
	v_exp_f32_e32 v19, v19
	v_mul_f32_e64 v6, v6, v36
	v_mul_f32_e64 v7, v7, v36
	v_add_f32_e32 v18, 1.0, v18
	v_add_f32_e32 v19, 1.0, v19
	v_rcp_f32_e32 v18, v18
	v_rcp_f32_e32 v19, v19
	s_nop 0
	v_mul_f32_e64 v16, v18, v16
	v_mul_f32_e64 v17, v19, v17
	v_lshlrev_b32_e32 v18, 16, v49
	v_and_b32_e32 v19, 0xffff0000, v49
	v_mul_f32_e64 v16, v20, v16
	v_mul_f32_e64 v17, v21, v17
	v_mul_f32_e32 v20, 0xbfb8aa3b, v18
	v_mul_f32_e32 v21, 0xbfb8aa3b, v19
	v_exp_f32_e32 v20, v20
	v_exp_f32_e32 v21, v21
	v_cvt_pk_bf16_f32 v16, v16, v17
	v_add_f32_e32 v20, 1.0, v20
	v_add_f32_e32 v21, 1.0, v21
	v_rcp_f32_e32 v20, v20
	v_rcp_f32_e32 v21, v21
	s_nop 0
	v_mul_f32_e64 v18, v20, v18
	v_mul_f32_e64 v19, v21, v19
	v_mul_f32_e64 v18, v22, v18
	v_mul_f32_e64 v19, v23, v19
	v_mul_f32_e64 v20, v24, v36
	v_mul_f32_e64 v21, v25, v36
	v_cvt_pk_bf16_f32 v17, v18, v19
	global_store_dwordx2 v[32:33], v[16:17], off offset:16
	v_lshlrev_b32_e32 v16, 16, v46
	v_and_b32_e32 v17, 0xffff0000, v46
	v_mul_f32_e32 v18, 0xbfb8aa3b, v16
	v_mul_f32_e32 v19, 0xbfb8aa3b, v17
	v_exp_f32_e32 v18, v18
	v_exp_f32_e32 v19, v19
	v_mul_f32_e64 v22, v26, v36
	v_mul_f32_e64 v23, v27, v36
	v_add_f32_e32 v18, 1.0, v18
	v_add_f32_e32 v19, 1.0, v19
	v_rcp_f32_e32 v18, v18
	v_rcp_f32_e32 v19, v19
	s_nop 0
	v_mul_f32_e64 v16, v18, v16
	v_mul_f32_e64 v17, v19, v17
	v_lshlrev_b32_e32 v18, 16, v47
	v_and_b32_e32 v19, 0xffff0000, v47
	v_mul_f32_e64 v16, v20, v16
	v_mul_f32_e64 v17, v21, v17
	v_mul_f32_e32 v20, 0xbfb8aa3b, v18
	v_mul_f32_e32 v21, 0xbfb8aa3b, v19
	v_exp_f32_e32 v20, v20
	v_exp_f32_e32 v21, v21
	v_cvt_pk_bf16_f32 v16, v16, v17
	v_add_f32_e32 v20, 1.0, v20
	v_add_f32_e32 v21, 1.0, v21
	v_rcp_f32_e32 v20, v20
	v_rcp_f32_e32 v21, v21
	s_nop 0
	v_mul_f32_e64 v18, v20, v18
	v_mul_f32_e64 v19, v21, v19
	v_mul_f32_e64 v18, v22, v18
	v_mul_f32_e64 v19, v23, v19
	v_mul_f32_e64 v20, v28, v36
	v_mul_f32_e64 v21, v29, v36
	v_cvt_pk_bf16_f32 v17, v18, v19
	global_store_dwordx2 v[32:33], v[16:17], off offset:32
	v_lshlrev_b32_e32 v16, 16, v44
	v_and_b32_e32 v17, 0xffff0000, v44
	v_mul_f32_e32 v18, 0xbfb8aa3b, v16
	v_mul_f32_e32 v19, 0xbfb8aa3b, v17
	v_exp_f32_e32 v18, v18
	v_exp_f32_e32 v19, v19
	v_mul_f32_e64 v22, v30, v36
	v_mul_f32_e64 v23, v31, v36
	v_add_f32_e32 v18, 1.0, v18
	v_add_f32_e32 v19, 1.0, v19
	v_rcp_f32_e32 v18, v18
	v_rcp_f32_e32 v19, v19
	s_nop 0
	v_mul_f32_e64 v16, v18, v16
	v_mul_f32_e64 v17, v19, v17
	v_lshlrev_b32_e32 v18, 16, v45
	v_and_b32_e32 v19, 0xffff0000, v45
	v_mul_f32_e64 v16, v20, v16
	v_mul_f32_e64 v17, v21, v17
	v_mul_f32_e32 v20, 0xbfb8aa3b, v18
	v_mul_f32_e32 v21, 0xbfb8aa3b, v19
	v_exp_f32_e32 v20, v20
	v_exp_f32_e32 v21, v21
	v_cvt_pk_bf16_f32 v16, v16, v17
	v_add_f32_e32 v20, 1.0, v20
	v_add_f32_e32 v21, 1.0, v21
	v_rcp_f32_e32 v20, v20
	v_rcp_f32_e32 v21, v21
	s_nop 0
	v_mul_f32_e64 v18, v20, v18
	v_mul_f32_e64 v19, v21, v19
	v_mul_f32_e64 v18, v22, v18
	v_mul_f32_e64 v19, v23, v19
	v_cvt_pk_bf16_f32 v17, v18, v19
	global_store_dwordx2 v[32:33], v[16:17], off offset:48
	v_lshlrev_b32_e32 v16, 16, v42
	v_and_b32_e32 v17, 0xffff0000, v42
	v_mul_f32_e32 v18, 0xbfb8aa3b, v16
	v_mul_f32_e32 v19, 0xbfb8aa3b, v17
	v_exp_f32_e32 v18, v18
	v_exp_f32_e32 v19, v19
	v_add_f32_e32 v18, 1.0, v18
	v_add_f32_e32 v19, 1.0, v19
	v_rcp_f32_e32 v18, v18
	v_rcp_f32_e32 v19, v19
	s_nop 0
	v_mul_f32_e64 v16, v18, v16
	v_mul_f32_e64 v17, v19, v17
	v_mul_f32_e64 v0, v0, v16
	v_mul_f32_e64 v1, v1, v17
	v_lshlrev_b32_e32 v16, 16, v43
	v_and_b32_e32 v17, 0xffff0000, v43
	v_mul_f32_e32 v18, 0xbfb8aa3b, v16
	v_mul_f32_e32 v19, 0xbfb8aa3b, v17
	v_exp_f32_e32 v18, v18
	v_exp_f32_e32 v19, v19
	v_cvt_pk_bf16_f32 v0, v0, v1
	v_add_f32_e32 v18, 1.0, v18
	v_add_f32_e32 v19, 1.0, v19
	v_rcp_f32_e32 v18, v18
	v_rcp_f32_e32 v19, v19
	s_nop 0
	v_mul_f32_e64 v16, v18, v16
	v_mul_f32_e64 v17, v19, v17
	v_mul_f32_e64 v2, v2, v16
	v_mul_f32_e64 v3, v3, v17
	v_cvt_pk_bf16_f32 v1, v2, v3
	global_store_dwordx2 v[32:33], v[0:1], off offset:64
	v_lshlrev_b32_e32 v0, 16, v40
	v_and_b32_e32 v1, 0xffff0000, v40
	v_mul_f32_e32 v2, 0xbfb8aa3b, v0
	v_mul_f32_e32 v3, 0xbfb8aa3b, v1
	v_exp_f32_e32 v2, v2
	v_exp_f32_e32 v3, v3
	v_add_f32_e32 v2, 1.0, v2
	v_add_f32_e32 v3, 1.0, v3
	v_rcp_f32_e32 v2, v2
	v_rcp_f32_e32 v3, v3
	s_nop 0
	v_mul_f32_e64 v0, v2, v0
	v_mul_f32_e64 v1, v3, v1
	v_lshlrev_b32_e32 v2, 16, v41
	v_and_b32_e32 v3, 0xffff0000, v41
	v_mul_f32_e64 v0, v4, v0
	v_mul_f32_e64 v1, v5, v1
	v_mul_f32_e32 v4, 0xbfb8aa3b, v2
	v_mul_f32_e32 v5, 0xbfb8aa3b, v3
	v_exp_f32_e32 v4, v4
	v_exp_f32_e32 v5, v5
	v_cvt_pk_bf16_f32 v0, v0, v1
	v_add_f32_e32 v4, 1.0, v4
	v_add_f32_e32 v5, 1.0, v5
	v_rcp_f32_e32 v4, v4
	v_rcp_f32_e32 v5, v5
	s_nop 0
	v_mul_f32_e64 v2, v4, v2
	v_mul_f32_e64 v3, v5, v3
	v_mul_f32_e64 v2, v6, v2
	v_mul_f32_e64 v3, v7, v3
	v_mul_f32_e64 v4, v8, v36
	v_mul_f32_e64 v5, v9, v36
	v_cvt_pk_bf16_f32 v1, v2, v3
	global_store_dwordx2 v[32:33], v[0:1], off offset:80
	v_lshlrev_b32_e32 v0, 16, v38
	v_and_b32_e32 v1, 0xffff0000, v38
	v_mul_f32_e32 v2, 0xbfb8aa3b, v0
	v_mul_f32_e32 v3, 0xbfb8aa3b, v1
	v_exp_f32_e32 v2, v2
	v_exp_f32_e32 v3, v3
	v_mul_f32_e64 v6, v10, v36
	v_mul_f32_e64 v7, v11, v36
	v_add_f32_e32 v2, 1.0, v2
	v_add_f32_e32 v3, 1.0, v3
	v_rcp_f32_e32 v2, v2
	v_rcp_f32_e32 v3, v3
	s_nop 0
	v_mul_f32_e64 v0, v2, v0
	v_mul_f32_e64 v1, v3, v1
	v_lshlrev_b32_e32 v2, 16, v39
	v_and_b32_e32 v3, 0xffff0000, v39
	v_mul_f32_e64 v0, v4, v0
	v_mul_f32_e64 v1, v5, v1
	v_mul_f32_e32 v4, 0xbfb8aa3b, v2
	v_mul_f32_e32 v5, 0xbfb8aa3b, v3
	v_exp_f32_e32 v4, v4
	v_exp_f32_e32 v5, v5
	v_cvt_pk_bf16_f32 v0, v0, v1
	v_add_f32_e32 v4, 1.0, v4
	v_add_f32_e32 v5, 1.0, v5
	v_rcp_f32_e32 v4, v4
	v_rcp_f32_e32 v5, v5
	s_nop 0
	v_mul_f32_e64 v2, v4, v2
	v_mul_f32_e64 v3, v5, v3
	v_mul_f32_e64 v2, v6, v2
	v_mul_f32_e64 v3, v7, v3
	v_mul_f32_e64 v4, v12, v36
	v_mul_f32_e64 v5, v13, v36
	v_cvt_pk_bf16_f32 v1, v2, v3
	global_store_dwordx2 v[32:33], v[0:1], off offset:96
	v_and_b32_e32 v1, 0xffff0000, v34
	v_mul_f32_e32 v2, 0xbfb8aa3b, v1
	v_exp_f32_e32 v2, v2
	v_lshlrev_b32_e32 v0, 16, v34
	v_mul_f32_e64 v6, v14, v36
	v_mul_f32_e64 v7, v15, v36
	v_add_f32_e32 v2, 1.0, v2
	v_rcp_f32_e32 v3, v2
	v_mul_f32_e32 v2, 0xbfb8aa3b, v0
	v_exp_f32_e32 v2, v2
	s_nop 0
	v_add_f32_e32 v2, 1.0, v2
	v_rcp_f32_e32 v2, v2
	s_nop 0
	v_mul_f32_e64 v0, v2, v0
	v_mul_f32_e64 v1, v3, v1
	v_lshlrev_b32_e32 v2, 16, v35
	v_and_b32_e32 v3, 0xffff0000, v35
	v_mul_f32_e64 v0, v4, v0
	v_mul_f32_e64 v1, v5, v1
	v_mul_f32_e32 v4, 0xbfb8aa3b, v2
	v_mul_f32_e32 v5, 0xbfb8aa3b, v3
	v_exp_f32_e32 v4, v4
	v_exp_f32_e32 v5, v5
	v_cvt_pk_bf16_f32 v0, v0, v1
	v_add_f32_e32 v4, 1.0, v4
	v_add_f32_e32 v5, 1.0, v5
	v_rcp_f32_e32 v4, v4
	v_rcp_f32_e32 v5, v5
	s_nop 0
	v_mul_f32_e64 v2, v4, v2
	v_mul_f32_e64 v3, v5, v3
	v_mul_f32_e64 v2, v6, v2
	v_mul_f32_e64 v3, v7, v3
	v_cvt_pk_bf16_f32 v1, v2, v3
	global_store_dwordx2 v[32:33], v[0:1], off offset:112
	s_waitcnt lgkmcnt(0)
	s_barrier

.LBB0_598:
	v_and_b32_e32 v35, 64, v188
	v_xor_b32_e32 v34, 32, v188
	v_add_u32_e32 v35, 64, v35
	v_cmp_lt_i32_e32 vcc, v34, v35
	v_mov_b64_e32 v[32:33], s[6:7]
	v_mad_i64_i32 v[32:33], s[0:1], v160, s97, v[32:33]
	v_cndmask_b32_e32 v34, v188, v34, vcc
	v_lshlrev_b32_e32 v34, 2, v34
	ds_bpermute_b32 v34, v34, v157
	s_lshl_b32 s84, s24, 7
	v_lshl_add_u64 v[32:33], v[32:33], 0, s[84:85]
	s_mov_b64 s[0:1], 0x7c01c00
	s_mov_b32 s52, s23
	s_waitcnt lgkmcnt(0)
	v_add_f32_e32 v36, v157, v34
	v_mul_u32_u24_e32 v34, 0x1c00, v162
	v_lshlrev_b32_e32 v112, 1, v34
	v_lshl_add_u64 v[32:33], v[32:33], 0, v[112:113]
	v_lshlrev_b32_e32 v112, 3, v161
	v_lshl_add_u64 v[34:35], v[32:33], 0, v[112:113]
	v_lshl_add_u64 v[32:33], v[34:35], 0, s[0:1]
	s_mov_b32 s0, 0x7c01000
	v_add_co_u32_e32 v50, vcc, s0, v34
	v_div_scale_f32 v37, s[0:1], v36, v36, 1.0
	s_nop 0
	v_addc_co_u32_e32 v51, vcc, 0, v35, vcc
	global_load_dwordx2 v[52:53], v[50:51], off offset:3072
	global_load_dwordx2 v[48:49], v[32:33], off offset:16
	global_load_dwordx2 v[46:47], v[32:33], off offset:32
	global_load_dwordx2 v[44:45], v[32:33], off offset:48
	global_load_dwordx2 v[42:43], v[32:33], off offset:64
	global_load_dwordx2 v[40:41], v[32:33], off offset:80
	global_load_dwordx2 v[38:39], v[32:33], off offset:96
	global_load_dwordx2 v[34:35], v[32:33], off offset:112
	v_rcp_f32_e32 v54, v37
	v_mov_b32_e32 v190, v160
	s_mov_b32 s53, s22
	s_mov_b32 s54, s21
	v_fma_f32 v55, -v37, v54, 1.0
	v_fmac_f32_e32 v54, v55, v54
	v_div_scale_f32 v55, vcc, 1.0, v36, 1.0
	v_mul_f32_e32 v56, v55, v54
	v_fma_f32 v57, -v37, v56, v55
	v_fmac_f32_e32 v56, v57, v54
	v_fma_f32 v37, -v37, v56, v55
	v_div_fmas_f32 v37, v37, v54, v56
	v_div_fixup_f32 v36, v37, v36, 1.0
	s_waitcnt vmcnt(0) lgkmcnt(0)
	v_lshlrev_b32_e32 v54, 16, v52
	v_mul_f32_e32 v37, 0xbfb8aa3b, v54
	v_exp_f32_e32 v37, v37
	v_and_b32_e32 v55, 0xffff0000, v52
	v_lshlrev_b32_e32 v52, 16, v53
	v_and_b32_e32 v53, 0xffff0000, v53
	v_add_f32_e32 v37, 1.0, v37
	v_rcp_f32_e32 v56, v37
	v_mul_f32_e64 v16, v16, v36
	v_mul_f32_e64 v17, v17, v36
	v_mul_f32_e32 v37, 0xbfb8aa3b, v55
	v_exp_f32_e32 v37, v37
	s_nop 0
	v_add_f32_e32 v37, 1.0, v37
	v_rcp_f32_e32 v57, v37
	v_mul_f32_e32 v37, 0xbfb8aa3b, v52
	v_exp_f32_e32 v37, v37
	v_mul_f32_e64 v54, v56, v54
	v_mul_f32_e64 v55, v57, v55
	v_mul_f32_e64 v16, v16, v54
	v_mul_f32_e64 v17, v17, v55
	v_add_f32_e32 v37, 1.0, v37
	v_rcp_f32_e32 v54, v37
	v_mul_f32_e64 v18, v18, v36
	v_mul_f32_e64 v19, v19, v36
	v_mul_f32_e32 v37, 0xbfb8aa3b, v53
	v_exp_f32_e32 v37, v37
	v_cvt_pk_bf16_f32 v16, v16, v17
	v_add_f32_e32 v37, 1.0, v37
	v_rcp_f32_e32 v55, v37
	v_mul_f32_e64 v20, v20, v36
	v_mul_f32_e64 v21, v21, v36
	v_mul_f32_e64 v22, v22, v36
	v_mul_f32_e64 v23, v23, v36
	v_mul_f32_e64 v0, v0, v36
	v_mul_f32_e64 v1, v1, v36
	v_mul_f32_e64 v52, v54, v52
	v_mul_f32_e64 v53, v55, v53
	v_mul_f32_e64 v2, v2, v36
	v_mul_f32_e64 v3, v3, v36
	v_mul_f32_e64 v18, v18, v52
	v_mul_f32_e64 v19, v19, v53
	v_mul_f32_e64 v4, v4, v36
	v_mul_f32_e64 v5, v5, v36
	v_cvt_pk_bf16_f32 v17, v18, v19
	global_store_dwordx2 v[50:51], v[16:17], off offset:3072
	v_lshlrev_b32_e32 v16, 16, v48
	v_and_b32_e32 v17, 0xffff0000, v48
	v_mul_f32_e32 v18, 0xbfb8aa3b, v16
	v_mul_f32_e32 v19, 0xbfb8aa3b, v17
	v_exp_f32_e32 v18, v18
	v_exp_f32_e32 v19, v19
	v_mul_f32_e64 v6, v6, v36
	v_mul_f32_e64 v7, v7, v36
	v_add_f32_e32 v18, 1.0, v18
	v_add_f32_e32 v19, 1.0, v19
	v_rcp_f32_e32 v18, v18
	v_rcp_f32_e32 v19, v19
	s_nop 0
	v_mul_f32_e64 v16, v18, v16
	v_mul_f32_e64 v17, v19, v17
	v_lshlrev_b32_e32 v18, 16, v49
	v_and_b32_e32 v19, 0xffff0000, v49
	v_mul_f32_e64 v16, v20, v16
	v_mul_f32_e64 v17, v21, v17
	v_mul_f32_e32 v20, 0xbfb8aa3b, v18
	v_mul_f32_e32 v21, 0xbfb8aa3b, v19
	v_exp_f32_e32 v20, v20
	v_exp_f32_e32 v21, v21
	v_cvt_pk_bf16_f32 v16, v16, v17
	v_add_f32_e32 v20, 1.0, v20
	v_add_f32_e32 v21, 1.0, v21
	v_rcp_f32_e32 v20, v20
	v_rcp_f32_e32 v21, v21
	s_nop 0
	v_mul_f32_e64 v18, v20, v18
	v_mul_f32_e64 v19, v21, v19
	v_mul_f32_e64 v18, v22, v18
	v_mul_f32_e64 v19, v23, v19
	v_mul_f32_e64 v20, v24, v36
	v_mul_f32_e64 v21, v25, v36
	v_cvt_pk_bf16_f32 v17, v18, v19
	global_store_dwordx2 v[32:33], v[16:17], off offset:16
	v_lshlrev_b32_e32 v16, 16, v46
	v_and_b32_e32 v17, 0xffff0000, v46
	v_mul_f32_e32 v18, 0xbfb8aa3b, v16
	v_mul_f32_e32 v19, 0xbfb8aa3b, v17
	v_exp_f32_e32 v18, v18
	v_exp_f32_e32 v19, v19
	v_mul_f32_e64 v22, v26, v36
	v_mul_f32_e64 v23, v27, v36
	v_add_f32_e32 v18, 1.0, v18
	v_add_f32_e32 v19, 1.0, v19
	v_rcp_f32_e32 v18, v18
	v_rcp_f32_e32 v19, v19
	s_nop 0
	v_mul_f32_e64 v16, v18, v16
	v_mul_f32_e64 v17, v19, v17
	v_lshlrev_b32_e32 v18, 16, v47
	v_and_b32_e32 v19, 0xffff0000, v47
	v_mul_f32_e64 v16, v20, v16
	v_mul_f32_e64 v17, v21, v17
	v_mul_f32_e32 v20, 0xbfb8aa3b, v18
	v_mul_f32_e32 v21, 0xbfb8aa3b, v19
	v_exp_f32_e32 v20, v20
	v_exp_f32_e32 v21, v21
	v_cvt_pk_bf16_f32 v16, v16, v17
	v_add_f32_e32 v20, 1.0, v20
	v_add_f32_e32 v21, 1.0, v21
	v_rcp_f32_e32 v20, v20
	v_rcp_f32_e32 v21, v21
	s_nop 0
	v_mul_f32_e64 v18, v20, v18
	v_mul_f32_e64 v19, v21, v19
	v_mul_f32_e64 v18, v22, v18
	v_mul_f32_e64 v19, v23, v19
	v_mul_f32_e64 v20, v28, v36
	v_mul_f32_e64 v21, v29, v36
	v_cvt_pk_bf16_f32 v17, v18, v19
	global_store_dwordx2 v[32:33], v[16:17], off offset:32
	v_lshlrev_b32_e32 v16, 16, v44
	v_and_b32_e32 v17, 0xffff0000, v44
	v_mul_f32_e32 v18, 0xbfb8aa3b, v16
	v_mul_f32_e32 v19, 0xbfb8aa3b, v17
	v_exp_f32_e32 v18, v18
	v_exp_f32_e32 v19, v19
	v_mul_f32_e64 v22, v30, v36
	v_mul_f32_e64 v23, v31, v36
	v_add_f32_e32 v18, 1.0, v18
	v_add_f32_e32 v19, 1.0, v19
	v_rcp_f32_e32 v18, v18
	v_rcp_f32_e32 v19, v19
	s_nop 0
	v_mul_f32_e64 v16, v18, v16
	v_mul_f32_e64 v17, v19, v17
	v_lshlrev_b32_e32 v18, 16, v45
	v_and_b32_e32 v19, 0xffff0000, v45
	v_mul_f32_e64 v16, v20, v16
	v_mul_f32_e64 v17, v21, v17
	v_mul_f32_e32 v20, 0xbfb8aa3b, v18
	v_mul_f32_e32 v21, 0xbfb8aa3b, v19
	v_exp_f32_e32 v20, v20
	v_exp_f32_e32 v21, v21
	v_cvt_pk_bf16_f32 v16, v16, v17
	v_add_f32_e32 v20, 1.0, v20
	v_add_f32_e32 v21, 1.0, v21
	v_rcp_f32_e32 v20, v20
	v_rcp_f32_e32 v21, v21
	s_nop 0
	v_mul_f32_e64 v18, v20, v18
	v_mul_f32_e64 v19, v21, v19
	v_mul_f32_e64 v18, v22, v18
	v_mul_f32_e64 v19, v23, v19
	v_cvt_pk_bf16_f32 v17, v18, v19
	global_store_dwordx2 v[32:33], v[16:17], off offset:48
	v_lshlrev_b32_e32 v16, 16, v42
	v_and_b32_e32 v17, 0xffff0000, v42
	v_mul_f32_e32 v18, 0xbfb8aa3b, v16
	v_mul_f32_e32 v19, 0xbfb8aa3b, v17
	v_exp_f32_e32 v18, v18
	v_exp_f32_e32 v19, v19
	v_add_f32_e32 v18, 1.0, v18
	v_add_f32_e32 v19, 1.0, v19
	v_rcp_f32_e32 v18, v18
	v_rcp_f32_e32 v19, v19
	s_nop 0
	v_mul_f32_e64 v16, v18, v16
	v_mul_f32_e64 v17, v19, v17
	v_mul_f32_e64 v0, v0, v16
	v_mul_f32_e64 v1, v1, v17
	v_lshlrev_b32_e32 v16, 16, v43
	v_and_b32_e32 v17, 0xffff0000, v43
	v_mul_f32_e32 v18, 0xbfb8aa3b, v16
	v_mul_f32_e32 v19, 0xbfb8aa3b, v17
	v_exp_f32_e32 v18, v18
	v_exp_f32_e32 v19, v19
	v_cvt_pk_bf16_f32 v0, v0, v1
	v_add_f32_e32 v18, 1.0, v18
	v_add_f32_e32 v19, 1.0, v19
	v_rcp_f32_e32 v18, v18
	v_rcp_f32_e32 v19, v19
	s_nop 0
	v_mul_f32_e64 v16, v18, v16
	v_mul_f32_e64 v17, v19, v17
	v_mul_f32_e64 v2, v2, v16
	v_mul_f32_e64 v3, v3, v17
	v_cvt_pk_bf16_f32 v1, v2, v3
	global_store_dwordx2 v[32:33], v[0:1], off offset:64
	v_lshlrev_b32_e32 v0, 16, v40
	v_and_b32_e32 v1, 0xffff0000, v40
	v_mul_f32_e32 v2, 0xbfb8aa3b, v0
	v_mul_f32_e32 v3, 0xbfb8aa3b, v1
	v_exp_f32_e32 v2, v2
	v_exp_f32_e32 v3, v3
	v_add_f32_e32 v2, 1.0, v2
	v_add_f32_e32 v3, 1.0, v3
	v_rcp_f32_e32 v2, v2
	v_rcp_f32_e32 v3, v3
	s_nop 0
	v_mul_f32_e64 v0, v2, v0
	v_mul_f32_e64 v1, v3, v1
	v_lshlrev_b32_e32 v2, 16, v41
	v_and_b32_e32 v3, 0xffff0000, v41
	v_mul_f32_e64 v0, v4, v0
	v_mul_f32_e64 v1, v5, v1
	v_mul_f32_e32 v4, 0xbfb8aa3b, v2
	v_mul_f32_e32 v5, 0xbfb8aa3b, v3
	v_exp_f32_e32 v4, v4
	v_exp_f32_e32 v5, v5
	v_cvt_pk_bf16_f32 v0, v0, v1
	v_add_f32_e32 v4, 1.0, v4
	v_add_f32_e32 v5, 1.0, v5
	v_rcp_f32_e32 v4, v4
	v_rcp_f32_e32 v5, v5
	s_nop 0
	v_mul_f32_e64 v2, v4, v2
	v_mul_f32_e64 v3, v5, v3
	v_mul_f32_e64 v2, v6, v2
	v_mul_f32_e64 v3, v7, v3
	v_mul_f32_e64 v4, v8, v36
	v_mul_f32_e64 v5, v9, v36
	v_cvt_pk_bf16_f32 v1, v2, v3
	global_store_dwordx2 v[32:33], v[0:1], off offset:80
	v_lshlrev_b32_e32 v0, 16, v38
	v_and_b32_e32 v1, 0xffff0000, v38
	v_mul_f32_e32 v2, 0xbfb8aa3b, v0
	v_mul_f32_e32 v3, 0xbfb8aa3b, v1
	v_exp_f32_e32 v2, v2
	v_exp_f32_e32 v3, v3
	v_mul_f32_e64 v6, v10, v36
	v_mul_f32_e64 v7, v11, v36
	v_add_f32_e32 v2, 1.0, v2
	v_add_f32_e32 v3, 1.0, v3
	v_rcp_f32_e32 v2, v2
	v_rcp_f32_e32 v3, v3
	s_nop 0
	v_mul_f32_e64 v0, v2, v0
	v_mul_f32_e64 v1, v3, v1
	v_lshlrev_b32_e32 v2, 16, v39
	v_and_b32_e32 v3, 0xffff0000, v39
	v_mul_f32_e64 v0, v4, v0
	v_mul_f32_e64 v1, v5, v1
	v_mul_f32_e32 v4, 0xbfb8aa3b, v2
	v_mul_f32_e32 v5, 0xbfb8aa3b, v3
	v_exp_f32_e32 v4, v4
	v_exp_f32_e32 v5, v5
	v_cvt_pk_bf16_f32 v0, v0, v1
	v_add_f32_e32 v4, 1.0, v4
	v_add_f32_e32 v5, 1.0, v5
	v_rcp_f32_e32 v4, v4
	v_rcp_f32_e32 v5, v5
	s_nop 0
	v_mul_f32_e64 v2, v4, v2
	v_mul_f32_e64 v3, v5, v3
	v_mul_f32_e64 v2, v6, v2
	v_mul_f32_e64 v3, v7, v3
	v_mul_f32_e64 v4, v12, v36
	v_mul_f32_e64 v5, v13, v36
	v_cvt_pk_bf16_f32 v1, v2, v3
	global_store_dwordx2 v[32:33], v[0:1], off offset:96
	v_and_b32_e32 v1, 0xffff0000, v34
	v_mul_f32_e32 v2, 0xbfb8aa3b, v1
	v_exp_f32_e32 v2, v2
	v_lshlrev_b32_e32 v0, 16, v34
	v_mul_f32_e64 v6, v14, v36
	v_mul_f32_e64 v7, v15, v36
	v_add_f32_e32 v2, 1.0, v2
	v_rcp_f32_e32 v3, v2
	v_mul_f32_e32 v2, 0xbfb8aa3b, v0
	v_exp_f32_e32 v2, v2
	s_nop 0
	v_add_f32_e32 v2, 1.0, v2
	v_rcp_f32_e32 v2, v2
	s_nop 0
	v_mul_f32_e64 v0, v2, v0
	v_mul_f32_e64 v1, v3, v1
	v_lshlrev_b32_e32 v2, 16, v35
	v_and_b32_e32 v3, 0xffff0000, v35
	v_mul_f32_e64 v0, v4, v0
	v_mul_f32_e64 v1, v5, v1
	v_mul_f32_e32 v4, 0xbfb8aa3b, v2
	v_mul_f32_e32 v5, 0xbfb8aa3b, v3
	v_exp_f32_e32 v4, v4
	v_exp_f32_e32 v5, v5
	v_cvt_pk_bf16_f32 v0, v0, v1
	v_add_f32_e32 v4, 1.0, v4
	v_add_f32_e32 v5, 1.0, v5
	v_rcp_f32_e32 v4, v4
	v_rcp_f32_e32 v5, v5
	s_nop 0
	v_mul_f32_e64 v2, v4, v2
	v_mul_f32_e64 v3, v5, v3
	v_mul_f32_e64 v2, v6, v2
	v_mul_f32_e64 v3, v7, v3
	v_cvt_pk_bf16_f32 v1, v2, v3
	global_store_dwordx2 v[32:33], v[0:1], off offset:112
	s_waitcnt lgkmcnt(0)
	s_barrier
